# in-proj GEMM: first two k-phase waits after an epilogue allow the 16 epilogue stores to stay in flight (vmcnt 24) instead of draining them
# speedup vs baseline: 1.0244x; 1.0026x over previous
.LBB0_144:
	s_add_i32 m0, s23, 0x18000
	v_lshl_add_u64 v[6:7], v[6:7], 0, s[62:63]
	s_waitcnt vmcnt(2)
	s_barrier
	global_load_lds_dwordx4 v[6:7], off
	v_lshl_add_u64 v[6:7], v[8:9], 0, s[62:63]
	s_add_i32 m0, s23, 0x1a000
	s_add_i32 s27, s23, 0x8000
	global_load_lds_dwordx4 v[6:7], off
	v_lshl_add_u64 v[6:7], v[10:11], 0, s[62:63]
	s_mov_b32 m0, s27
	s_add_i32 s28, s23, 0xa000
	global_load_lds_dwordx4 v[6:7], off
	v_lshl_add_u64 v[6:7], v[12:13], 0, s[62:63]
	s_mov_b32 m0, s28
	s_lshl_b32 s5, s5, 5
	global_load_lds_dwordx4 v[6:7], off
	v_lshl_add_u64 v[6:7], v[2:3], 0, s[84:85]
	s_add_i32 m0, s23, 0x1c000
	v_lshl_add_u64 v[8:9], v[6:7], 0, v[138:139]
	global_load_lds_dwordx4 v[8:9], off
	v_lshl_add_u64 v[6:7], v[6:7], 0, v[134:135]
	s_add_i32 m0, s23, 0x1e000
	s_and_b32 s5, s5, 0x60
	global_load_lds_dwordx4 v[6:7], off
	v_lshrrev_b32_e32 v7, 1, v0
	v_and_b32_e32 v7, 24, v7
	v_and_b32_e32 v6, 15, v0
	v_lshlrev_b32_e32 v8, 1, v7
	v_lshlrev_b32_e32 v0, 2, v0
	v_lshl_or_b32 v162, s6, 6, v6
	v_lshl_or_b32 v6, v6, 6, v8
	s_lshl_b32 s6, s6, 13
	v_and_b32_e32 v0, 32, v0
	v_bitop3_b32 v8, v6, s6, v0 bitop3:0xde
	s_lshl_b32 s6, s5, 7
	v_bitop3_b32 v163, v6, s6, v0 bitop3:0xde
	v_lshlrev_b32_e32 v0, 14, v14
	v_and_b32_e32 v0, 0xffff8000, v0
	v_lshl_add_u32 v0, v15, 11, v0
	v_and_b32_e32 v6, 1, v14
	v_lshl_or_b32 v0, v6, 6, v0
	v_lshl_add_u32 v146, v16, 1, v0
	v_lshlrev_b32_e32 v0, 14, v18
	v_and_b32_e32 v0, 0xffff8000, v0
	s_mov_b64 s[8:9], 0x8b89000
	s_waitcnt vmcnt(6)
	v_lshl_add_u32 v0, v17, 11, v0
	v_and_b32_e32 v6, 1, v18
	v_lshl_add_u64 v[142:143], v[130:131], 0, s[8:9]
	s_mov_b64 s[8:9], 0x12b89000
	s_cmpk_lt_u32 s4, 0x100
	v_or_b32_e32 v164, s5, v7
	v_lshl_or_b32 v0, v6, 6, v0
	v_readlane_b32 s4, v254, 41
	s_movk_i32 s40, 0xec00
	v_lshl_add_u64 v[144:145], v[130:131], 0, s[8:9]
	s_cselect_b64 s[14:15], -1, 0
	v_mov_b32_e32 v147, v1
	v_lshl_add_u32 v148, v19, 1, v0
	v_mov_b32_e32 v149, v1
	s_mov_b32 s29, 0
	v_add_u32_e32 v165, 0, v8
	v_readlane_b32 s7, v254, 18
	s_mov_b32 s6, s4
	s_movk_i32 s34, 0x161
	s_movk_i32 s35, 0x9ff
	s_movk_i32 s36, 0x980
	s_mov_b32 s41, -1
	s_barrier
	v_readlane_b32 s5, v254, 42
	s_mov_b32 s98, 0
	s_branch .LBB0_147

.LBB0_146:
	s_mov_b32 s98, 1
	s_andn2_b64 vcc, exec, s[4:5]
	s_mov_b32 s7, s16
	s_mov_b32 s6, s18
	v_mov_b64_e32 v[2:3], v[152:153]
	v_mov_b64_e32 v[4:5], v[150:151]
	s_cbranch_vccz .LBB0_252

.LBB0_150:
	s_cmp_eq_u32 s4, 12
	s_cselect_b64 vcc, -1, 0
	s_add_i32 s5, 0, 0x10000
	v_lshl_add_u64 v[166:167], v[160:161], 0, s[88:89]
	v_add_u32_e32 v156, s5, v163
	s_add_i32 s8, 0, 0x14000
	v_cndmask_b32_e32 v195, v167, v155, vcc
	v_cndmask_b32_e32 v194, v166, v0, vcc
	ds_read_b128 v[166:169], v156
	ds_read_b128 v[170:173], v156 offset:1024
	ds_read_b128 v[174:177], v156 offset:2048
	ds_read_b128 v[178:181], v156 offset:3072
	v_add_u32_e32 v156, s8, v163
	ds_read_b128 v[182:185], v156
	ds_read_b128 v[186:189], v156 offset:1024
	ds_read_b128 v[190:193], v156 offset:2048
	ds_read_b128 v[200:203], v156 offset:3072
	v_cndmask_b32_e32 v237, v159, v157, vcc
	v_cndmask_b32_e32 v236, v158, v154, vcc
	v_lshl_add_u64 v[252:253], v[160:161], 0, v[148:149]
	s_add_i32 m0, s23, 0xc000
	ds_read_b128 v[204:207], v165
	ds_read_b128 v[208:211], v165 offset:1024
	ds_read_b128 v[212:215], v165 offset:2048
	ds_read_b128 v[216:219], v165 offset:3072
	ds_read_b128 v[220:223], v165 offset:4096
	ds_read_b128 v[224:227], v165 offset:5120
	ds_read_b128 v[228:231], v165 offset:6144
	ds_read_b128 v[232:235], v165 offset:7168
	global_load_lds_dwordx4 v[252:253], off
	v_lshl_add_u64 v[252:253], v[160:161], 0, v[146:147]
	s_add_i32 m0, s23, 0xe000
	s_nop 0
	global_load_lds_dwordx4 v[252:253], off
	s_cmp_lg_u32 s98, 0
	s_cbranch_scc1 .Lgr_g1_1
	s_waitcnt vmcnt(8)
.Lgr_g1_1:
	s_waitcnt vmcnt(24)
	s_waitcnt lgkmcnt(0)
	s_barrier
	s_setprio 1
	s_waitcnt lgkmcnt(0)
	v_mfma_f32_16x16x32_bf16 v[126:129], v[166:169], v[204:207], v[126:129]
	v_mfma_f32_16x16x32_bf16 v[122:125], v[174:177], v[204:207], v[122:125]
	v_mfma_f32_16x16x32_bf16 v[110:113], v[166:169], v[212:215], v[110:113]
	v_mfma_f32_16x16x32_bf16 v[106:109], v[174:177], v[212:215], v[106:109]
	v_mfma_f32_16x16x32_bf16 v[94:97], v[166:169], v[220:223], v[94:97]
	v_mfma_f32_16x16x32_bf16 v[90:93], v[174:177], v[220:223], v[90:93]
	v_mfma_f32_16x16x32_bf16 v[78:81], v[166:169], v[228:231], v[78:81]
	v_mfma_f32_16x16x32_bf16 v[74:77], v[174:177], v[228:231], v[74:77]
	v_mfma_f32_16x16x32_bf16 v[126:129], v[170:173], v[208:211], v[126:129]
	v_mfma_f32_16x16x32_bf16 v[122:125], v[178:181], v[208:211], v[122:125]
	v_mfma_f32_16x16x32_bf16 v[110:113], v[170:173], v[216:219], v[110:113]
	v_mfma_f32_16x16x32_bf16 v[106:109], v[178:181], v[216:219], v[106:109]
	v_mfma_f32_16x16x32_bf16 v[94:97], v[170:173], v[224:227], v[94:97]
	v_mfma_f32_16x16x32_bf16 v[90:93], v[178:181], v[224:227], v[90:93]
	v_mfma_f32_16x16x32_bf16 v[78:81], v[170:173], v[232:235], v[78:81]
	v_mfma_f32_16x16x32_bf16 v[74:77], v[178:181], v[232:235], v[74:77]
	s_setprio 0
	s_setprio 1
	v_mfma_f32_16x16x32_bf16 v[118:121], v[182:185], v[204:207], v[118:121]
	v_mfma_f32_16x16x32_bf16 v[114:117], v[190:193], v[204:207], v[114:117]
	v_mfma_f32_16x16x32_bf16 v[102:105], v[182:185], v[212:215], v[102:105]
	v_mfma_f32_16x16x32_bf16 v[98:101], v[190:193], v[212:215], v[98:101]
	v_mfma_f32_16x16x32_bf16 v[86:89], v[182:185], v[220:223], v[86:89]
	v_mfma_f32_16x16x32_bf16 v[82:85], v[190:193], v[220:223], v[82:85]
	v_mfma_f32_16x16x32_bf16 v[70:73], v[182:185], v[228:231], v[70:73]
	v_mfma_f32_16x16x32_bf16 v[66:69], v[190:193], v[228:231], v[66:69]
	v_mfma_f32_16x16x32_bf16 v[118:121], v[186:189], v[208:211], v[118:121]
	v_mfma_f32_16x16x32_bf16 v[114:117], v[200:203], v[208:211], v[114:117]
	v_mfma_f32_16x16x32_bf16 v[102:105], v[186:189], v[216:219], v[102:105]
	v_mfma_f32_16x16x32_bf16 v[98:101], v[200:203], v[216:219], v[98:101]
	v_mfma_f32_16x16x32_bf16 v[86:89], v[186:189], v[224:227], v[86:89]
	v_mfma_f32_16x16x32_bf16 v[82:85], v[200:203], v[224:227], v[82:85]
	v_mfma_f32_16x16x32_bf16 v[70:73], v[186:189], v[232:235], v[70:73]
	v_mfma_f32_16x16x32_bf16 v[66:69], v[200:203], v[232:235], v[66:69]
	s_setprio 0
	s_barrier
	s_add_i32 s5, s5, s22
	v_lshl_add_u64 v[252:253], v[236:237], 0, v[138:139]
	s_mov_b32 m0, s5
	ds_read_b128 v[204:207], v165 offset:16384
	ds_read_b128 v[208:211], v165 offset:17408
	ds_read_b128 v[212:215], v165 offset:18432
	ds_read_b128 v[216:219], v165 offset:19456
	ds_read_b128 v[220:223], v165 offset:20480
	ds_read_b128 v[224:227], v165 offset:21504
	ds_read_b128 v[228:231], v165 offset:22528
	ds_read_b128 v[232:235], v165 offset:23552
	global_load_lds_dwordx4 v[252:253], off
	v_lshl_add_u64 v[242:243], v[236:237], 0, v[134:135]
	s_add_i32 m0, s5, 0x2000
	v_lshl_add_u64 v[244:245], v[236:237], 0, s[64:65]
	s_add_i32 s5, s8, s22
	global_load_lds_dwordx4 v[242:243], off
	v_lshl_add_u64 v[238:239], v[244:245], 0, v[138:139]
	s_mov_b32 m0, s5
	s_nop 0
	global_load_lds_dwordx4 v[238:239], off
	v_lshl_add_u64 v[238:239], v[244:245], 0, v[134:135]
	s_add_i32 m0, s5, 0x2000
	v_lshl_add_u64 v[244:245], v[194:195], 0, v[136:137]
	global_load_lds_dwordx4 v[238:239], off
	v_lshl_add_u64 v[238:239], v[194:195], 0, v[140:141]
	s_mov_b32 m0, s23
	s_nop 0
	global_load_lds_dwordx4 v[238:239], off
	s_mov_b32 m0, s24
	s_nop 0
	global_load_lds_dwordx4 v[244:245], off
	s_cmp_lg_u32 s98, 0
	s_cbranch_scc1 .Lgr_g1_2
	s_waitcnt vmcnt(8)
.Lgr_g1_2:
	s_waitcnt vmcnt(24)
	s_mov_b32 s98, 0
	s_waitcnt lgkmcnt(0)
	s_barrier
	s_setprio 1
	s_waitcnt lgkmcnt(0)
	v_mfma_f32_16x16x32_bf16 v[62:65], v[166:169], v[204:207], v[62:65]
	v_mfma_f32_16x16x32_bf16 v[58:61], v[174:177], v[204:207], v[58:61]
	v_mfma_f32_16x16x32_bf16 v[46:49], v[166:169], v[212:215], v[46:49]
	v_mfma_f32_16x16x32_bf16 v[42:45], v[174:177], v[212:215], v[42:45]
	v_mfma_f32_16x16x32_bf16 v[30:33], v[166:169], v[220:223], v[30:33]
	v_mfma_f32_16x16x32_bf16 v[26:29], v[174:177], v[220:223], v[26:29]
	v_mfma_f32_16x16x32_bf16 v[14:17], v[166:169], v[228:231], v[14:17]
	v_mfma_f32_16x16x32_bf16 v[10:13], v[174:177], v[228:231], v[10:13]
	v_mfma_f32_16x16x32_bf16 v[62:65], v[170:173], v[208:211], v[62:65]
	v_mfma_f32_16x16x32_bf16 v[58:61], v[178:181], v[208:211], v[58:61]
	v_mfma_f32_16x16x32_bf16 v[46:49], v[170:173], v[216:219], v[46:49]
	v_mfma_f32_16x16x32_bf16 v[42:45], v[178:181], v[216:219], v[42:45]
	v_mfma_f32_16x16x32_bf16 v[30:33], v[170:173], v[224:227], v[30:33]
	v_mfma_f32_16x16x32_bf16 v[26:29], v[178:181], v[224:227], v[26:29]
	v_mfma_f32_16x16x32_bf16 v[14:17], v[170:173], v[232:235], v[14:17]
	v_mfma_f32_16x16x32_bf16 v[10:13], v[178:181], v[232:235], v[10:13]
	s_setprio 0
	s_setprio 1
	v_mfma_f32_16x16x32_bf16 v[54:57], v[182:185], v[204:207], v[54:57]
	v_mfma_f32_16x16x32_bf16 v[50:53], v[190:193], v[204:207], v[50:53]
	v_mfma_f32_16x16x32_bf16 v[38:41], v[182:185], v[212:215], v[38:41]
	v_mfma_f32_16x16x32_bf16 v[34:37], v[190:193], v[212:215], v[34:37]
	v_mfma_f32_16x16x32_bf16 v[22:25], v[182:185], v[220:223], v[22:25]
	v_mfma_f32_16x16x32_bf16 v[18:21], v[190:193], v[220:223], v[18:21]
	v_mfma_f32_16x16x32_bf16 v[6:9], v[182:185], v[228:231], v[6:9]
	v_mfma_f32_16x16x32_bf16 v[2:5], v[190:193], v[228:231], v[2:5]
	v_mfma_f32_16x16x32_bf16 v[54:57], v[186:189], v[208:211], v[54:57]
	v_mfma_f32_16x16x32_bf16 v[50:53], v[200:203], v[208:211], v[50:53]
	v_mfma_f32_16x16x32_bf16 v[38:41], v[186:189], v[216:219], v[38:41]
	v_mfma_f32_16x16x32_bf16 v[34:37], v[200:203], v[216:219], v[34:37]
	v_mfma_f32_16x16x32_bf16 v[22:25], v[186:189], v[224:227], v[22:25]
	v_mfma_f32_16x16x32_bf16 v[18:21], v[200:203], v[224:227], v[18:21]
	v_mfma_f32_16x16x32_bf16 v[6:9], v[186:189], v[232:235], v[6:9]
	v_mfma_f32_16x16x32_bf16 v[2:5], v[200:203], v[232:235], v[2:5]
	s_setprio 0
	s_barrier
	s_add_i32 s5, 0, 0x18000
	v_add_u32_e32 v156, s5, v163
	s_add_i32 s8, 0, 0x1c000
	ds_read_b128 v[166:169], v156
	ds_read_b128 v[170:173], v156 offset:1024
	ds_read_b128 v[174:177], v156 offset:2048
	ds_read_b128 v[178:181], v156 offset:3072
	v_add_u32_e32 v156, s8, v163
	ds_read_b128 v[182:185], v156
	ds_read_b128 v[186:189], v156 offset:1024
	ds_read_b128 v[190:193], v156 offset:2048
	ds_read_b128 v[200:203], v156 offset:3072
	v_lshl_add_u64 v[194:195], v[194:195], 0, s[64:65]
	s_mov_b32 m0, s25
	v_lshl_add_u64 v[240:241], v[194:195], 0, v[140:141]
	ds_read_b128 v[204:207], v165 offset:32768
	ds_read_b128 v[208:211], v165 offset:33792
	ds_read_b128 v[212:215], v165 offset:34816
	ds_read_b128 v[216:219], v165 offset:35840
	ds_read_b128 v[220:223], v165 offset:36864
	ds_read_b128 v[224:227], v165 offset:37888
	ds_read_b128 v[228:231], v165 offset:38912
	ds_read_b128 v[232:235], v165 offset:39936
	global_load_lds_dwordx4 v[240:241], off
	v_lshl_add_u64 v[194:195], v[194:195], 0, v[136:137]
	s_mov_b32 m0, s26
	s_nop 0
	global_load_lds_dwordx4 v[194:195], off
	s_waitcnt vmcnt(8)
	s_waitcnt lgkmcnt(0)
	s_barrier
	s_setprio 1
	s_waitcnt lgkmcnt(0)
	v_mfma_f32_16x16x32_bf16 v[126:129], v[166:169], v[204:207], v[126:129]
	v_mfma_f32_16x16x32_bf16 v[122:125], v[174:177], v[204:207], v[122:125]
	v_mfma_f32_16x16x32_bf16 v[110:113], v[166:169], v[212:215], v[110:113]
	v_mfma_f32_16x16x32_bf16 v[106:109], v[174:177], v[212:215], v[106:109]
	v_mfma_f32_16x16x32_bf16 v[94:97], v[166:169], v[220:223], v[94:97]
	v_mfma_f32_16x16x32_bf16 v[90:93], v[174:177], v[220:223], v[90:93]
	v_mfma_f32_16x16x32_bf16 v[78:81], v[166:169], v[228:231], v[78:81]
	v_mfma_f32_16x16x32_bf16 v[74:77], v[174:177], v[228:231], v[74:77]
	v_mfma_f32_16x16x32_bf16 v[126:129], v[170:173], v[208:211], v[126:129]
	v_mfma_f32_16x16x32_bf16 v[122:125], v[178:181], v[208:211], v[122:125]
	v_mfma_f32_16x16x32_bf16 v[110:113], v[170:173], v[216:219], v[110:113]
	v_mfma_f32_16x16x32_bf16 v[106:109], v[178:181], v[216:219], v[106:109]
	v_mfma_f32_16x16x32_bf16 v[94:97], v[170:173], v[224:227], v[94:97]
	v_mfma_f32_16x16x32_bf16 v[90:93], v[178:181], v[224:227], v[90:93]
	v_mfma_f32_16x16x32_bf16 v[78:81], v[170:173], v[232:235], v[78:81]
	v_mfma_f32_16x16x32_bf16 v[74:77], v[178:181], v[232:235], v[74:77]
	s_setprio 0
	s_setprio 1
	v_mfma_f32_16x16x32_bf16 v[118:121], v[182:185], v[204:207], v[118:121]
	v_mfma_f32_16x16x32_bf16 v[114:117], v[190:193], v[204:207], v[114:117]
	v_mfma_f32_16x16x32_bf16 v[102:105], v[182:185], v[212:215], v[102:105]
	v_mfma_f32_16x16x32_bf16 v[98:101], v[190:193], v[212:215], v[98:101]
	v_mfma_f32_16x16x32_bf16 v[86:89], v[182:185], v[220:223], v[86:89]
	v_mfma_f32_16x16x32_bf16 v[82:85], v[190:193], v[220:223], v[82:85]
	v_mfma_f32_16x16x32_bf16 v[70:73], v[182:185], v[228:231], v[70:73]
	v_mfma_f32_16x16x32_bf16 v[66:69], v[190:193], v[228:231], v[66:69]
	v_mfma_f32_16x16x32_bf16 v[118:121], v[186:189], v[208:211], v[118:121]
	v_mfma_f32_16x16x32_bf16 v[114:117], v[200:203], v[208:211], v[114:117]
	v_mfma_f32_16x16x32_bf16 v[102:105], v[186:189], v[216:219], v[102:105]
	v_mfma_f32_16x16x32_bf16 v[98:101], v[200:203], v[216:219], v[98:101]
	v_mfma_f32_16x16x32_bf16 v[86:89], v[186:189], v[224:227], v[86:89]
	v_mfma_f32_16x16x32_bf16 v[82:85], v[200:203], v[224:227], v[82:85]
	v_mfma_f32_16x16x32_bf16 v[70:73], v[186:189], v[232:235], v[70:73]
	v_mfma_f32_16x16x32_bf16 v[66:69], v[200:203], v[232:235], v[66:69]
	s_setprio 0
	s_barrier
	s_add_i32 s5, s5, s22
	v_lshl_add_u64 v[194:195], v[252:253], 0, s[62:63]
	s_mov_b32 m0, s5
	ds_read_b128 v[204:207], v165 offset:49152
	ds_read_b128 v[208:211], v165 offset:50176
	ds_read_b128 v[212:215], v165 offset:51200
	ds_read_b128 v[216:219], v165 offset:52224
	ds_read_b128 v[220:223], v165 offset:53248
	ds_read_b128 v[224:227], v165 offset:54272
	ds_read_b128 v[228:231], v165 offset:55296
	ds_read_b128 v[232:235], v165 offset:56320
	global_load_lds_dwordx4 v[194:195], off
	v_lshl_add_u64 v[194:195], v[242:243], 0, s[62:63]
	s_add_i32 m0, s5, 0x2000
	s_add_i32 s5, s8, s22
	global_load_lds_dwordx4 v[194:195], off
	v_lshl_add_u64 v[194:195], v[236:237], 0, s[84:85]
	v_lshl_add_u64 v[236:237], v[194:195], 0, v[138:139]
	s_mov_b32 m0, s5
	v_lshl_add_u64 v[194:195], v[194:195], 0, v[134:135]
	global_load_lds_dwordx4 v[236:237], off
	s_add_i32 m0, s5, 0x2000
	s_nop 0
	global_load_lds_dwordx4 v[194:195], off
	v_lshl_add_u64 v[194:195], v[238:239], 0, s[62:63]
	s_mov_b32 m0, s27
	s_nop 0
	global_load_lds_dwordx4 v[194:195], off
	v_lshl_add_u64 v[194:195], v[244:245], 0, s[62:63]
	s_mov_b32 m0, s28
	s_nop 0
	global_load_lds_dwordx4 v[194:195], off
	s_waitcnt vmcnt(8)
	s_waitcnt lgkmcnt(0)
	s_barrier
	s_setprio 1
	s_waitcnt lgkmcnt(0)
	v_mfma_f32_16x16x32_bf16 v[62:65], v[166:169], v[204:207], v[62:65]
	v_mfma_f32_16x16x32_bf16 v[58:61], v[174:177], v[204:207], v[58:61]
	v_mfma_f32_16x16x32_bf16 v[46:49], v[166:169], v[212:215], v[46:49]
	v_mfma_f32_16x16x32_bf16 v[42:45], v[174:177], v[212:215], v[42:45]
	v_mfma_f32_16x16x32_bf16 v[30:33], v[166:169], v[220:223], v[30:33]
	v_mfma_f32_16x16x32_bf16 v[26:29], v[174:177], v[220:223], v[26:29]
	v_mfma_f32_16x16x32_bf16 v[14:17], v[166:169], v[228:231], v[14:17]
	v_mfma_f32_16x16x32_bf16 v[10:13], v[174:177], v[228:231], v[10:13]
	v_mfma_f32_16x16x32_bf16 v[62:65], v[170:173], v[208:211], v[62:65]
	v_mfma_f32_16x16x32_bf16 v[58:61], v[178:181], v[208:211], v[58:61]
	v_mfma_f32_16x16x32_bf16 v[46:49], v[170:173], v[216:219], v[46:49]
	v_mfma_f32_16x16x32_bf16 v[42:45], v[178:181], v[216:219], v[42:45]
	v_mfma_f32_16x16x32_bf16 v[30:33], v[170:173], v[224:227], v[30:33]
	v_mfma_f32_16x16x32_bf16 v[26:29], v[178:181], v[224:227], v[26:29]
	v_mfma_f32_16x16x32_bf16 v[14:17], v[170:173], v[232:235], v[14:17]
	v_mfma_f32_16x16x32_bf16 v[10:13], v[178:181], v[232:235], v[10:13]
	s_setprio 0
	s_setprio 1
	v_mfma_f32_16x16x32_bf16 v[54:57], v[182:185], v[204:207], v[54:57]
	v_mfma_f32_16x16x32_bf16 v[50:53], v[190:193], v[204:207], v[50:53]
	v_mfma_f32_16x16x32_bf16 v[38:41], v[182:185], v[212:215], v[38:41]
	v_mfma_f32_16x16x32_bf16 v[34:37], v[190:193], v[212:215], v[34:37]
	v_mfma_f32_16x16x32_bf16 v[22:25], v[182:185], v[220:223], v[22:25]
	v_mfma_f32_16x16x32_bf16 v[18:21], v[190:193], v[220:223], v[18:21]
	v_mfma_f32_16x16x32_bf16 v[6:9], v[182:185], v[228:231], v[6:9]
	v_mfma_f32_16x16x32_bf16 v[2:5], v[190:193], v[228:231], v[2:5]
	v_mfma_f32_16x16x32_bf16 v[54:57], v[186:189], v[208:211], v[54:57]
	v_mfma_f32_16x16x32_bf16 v[50:53], v[200:203], v[208:211], v[50:53]
	v_mfma_f32_16x16x32_bf16 v[38:41], v[186:189], v[216:219], v[38:41]
	v_mfma_f32_16x16x32_bf16 v[34:37], v[200:203], v[216:219], v[34:37]
	v_mfma_f32_16x16x32_bf16 v[22:25], v[186:189], v[224:227], v[22:25]
	v_mfma_f32_16x16x32_bf16 v[18:21], v[200:203], v[224:227], v[18:21]
	v_mfma_f32_16x16x32_bf16 v[6:9], v[186:189], v[232:235], v[6:9]
	v_mfma_f32_16x16x32_bf16 v[2:5], v[200:203], v[232:235], v[2:5]
	s_setprio 0
	s_barrier
	s_add_i32 s4, s4, 2
	v_lshl_add_u64 v[158:159], v[158:159], 0, s[86:87]
	s_cmp_gt_u32 s4, 13
	v_lshl_add_u64 v[160:161], v[160:161], 0, s[86:87]
	s_cbranch_scc0 .LBB0_150
	s_and_b64 vcc, exec, s[14:15]
	s_cbranch_vccz .LBB0_153
	s_barrier
